# dropped the compiler's redundant s_nop 6 in the second tile's first P.V group (20+ issued instructions already separate the last QK MFMA from the exps that read its result)
# baseline (speedup 1.0000x reference)
; #define SBAR() __builtin_amdgcn_sched_barrier(0)
; __device__ __forceinline__ void qkt3(f32x16& p0, f32x16& p1, const bf16* Ks, const bf16x8* qr, int r32, int hi, const f32x16& cinit) {
;   { int cb = (hi * 8) * 2;
;     bf16x8 b0 = *reinterpret_cast<const bf16x8*>((const char*)Ks + KSWZ(r32, cb));
;     bf16x8 b1 = *reinterpret_cast<const bf16x8*>((const char*)Ks + KSWZ(32 + r32, cb));
;     p0 = __builtin_amdgcn_mfma_f32_32x32x16_bf16(b0, qr[0], cinit, 0, 0, 0);
;     p1 = __builtin_amdgcn_mfma_f32_32x32x16_bf16(b1, qr[0], cinit, 0, 0, 0); }
;   for (int d0 = 1; d0 < 8; ++d0) { int cb = (d0 * 16 + hi * 8) * 2;
;     bf16x8 b0 = *reinterpret_cast<const bf16x8*>((const char*)Ks + KSWZ(r32, cb));
;     bf16x8 b1 = *reinterpret_cast<const bf16x8*>((const char*)Ks + KSWZ(32 + r32, cb));
;     p0 = __builtin_amdgcn_mfma_f32_32x32x16_bf16(b0, qr[d0], p0, 0, 0, 0);
;     p1 = __builtin_amdgcn_mfma_f32_32x32x16_bf16(b1, qr[d0], p1, 0, 0, 0); }
; }
; __device__ __forceinline__ int v_st(int k, int c) { const int kk = (k & ~0xC) | ((k & 4) << 1) | ((k & 8) >> 1); return ((kk >> 3) * 4 + (c >> 5)) * 512 + ((kk & 7) * 32 + (c & 31)) * 2; }
; __device__ __forceinline__ int v_rd_base(int lane) { return ((lane & 3) << 3) | (((lane >> 2) & 3) << 6) | (((lane >> 4) & 1) << 5) | (((lane >> 5) & 1) << 8); }
; template <int OFF> __device__ __forceinline__ s16x4 tr_read(int vb) {
;   s16x4 r; asm volatile("ds_read_b64_tr_b16 %0, %1 offset:%2" : "=&v"(r) : "v"(vb), "i"(OFF) : "memory"); return r;
; }
; template <int D0> __device__ __forceinline__ void pv_one(f32x16& od, int vb, bf16x8 pa0, bf16x8 pa1, bf16x8 pa2, bf16x8 pa3) {
;   const s16x4 l0 = tr_read<v_rd_off(D0, 0, 0)>(vb), h0 = tr_read<v_rd_off(D0, 0, 1)>(vb), l1 = tr_read<v_rd_off(D0, 1, 0)>(vb), h1 = tr_read<v_rd_off(D0, 1, 1)>(vb);
;   const s16x4 l2 = tr_read<v_rd_off(D0, 2, 0)>(vb), h2 = tr_read<v_rd_off(D0, 2, 1)>(vb), l3 = tr_read<v_rd_off(D0, 3, 0)>(vb), h3 = tr_read<v_rd_off(D0, 3, 1)>(vb);
;   asm volatile("s_waitcnt lgkmcnt(0)" ::: "memory"); SBAR();
;     ...
;   od = __builtin_amdgcn_mfma_f32_32x32x16_bf16(pa0, PK(l0, h0), od, 0, 0, 0);
;   od = __builtin_amdgcn_mfma_f32_32x32x16_bf16(pa1, PK(l1, h1), od, 0, 0, 0);
;   od = __builtin_amdgcn_mfma_f32_32x32x16_bf16(pa2, PK(l2, h2), od, 0, 0, 0);
;   od = __builtin_amdgcn_mfma_f32_32x32x16_bf16(pa3, PK(l3, h3), od, 0, 0, 0);
;     ...
; }
.LBB0_117:
	s_lshl_b32 s49, s48, 14
	s_mov_b32 s53, s46
	s_mov_b32 s46, s54
	s_add_i32 s86, s90, s49
	s_and_b32 s87, s47, 2
	s_lshl_b32 s87, s87, 14
	s_add_i32 s87, s87, s90
	s_lshl_b32 s15, s53, 14
	s_lshl_b32 s14, s54, 14
	v_add_u32_e32 v238, s15, v157
	ds_read_b128 v[246:249], v238 offset:49152
	ds_read_b128 v[238:241], v238 offset:57344
	v_add_u32_e32 v228, s15, v177
	ds_read_b128 v[224:227], v228 offset:49152
	ds_read_b128 v[228:231], v228 offset:57344
	v_cvt_pk_bf16_f32 v185, v202, v204
	v_cvt_pk_bf16_f32 v191, v180, v182
	v_cvt_pk_bf16_f32 v181, v212, v214
	v_cvt_pk_bf16_f32 v187, v220, v222
	v_cvt_pk_bf16_f32 v189, v158, v166
	s_waitcnt lgkmcnt(2)
	v_mfma_f32_32x32x16_bf16 v[96:111], v[246:249], v[140:143], v[64:79]
	v_mfma_f32_32x32x16_bf16 v[80:95], v[238:241], v[140:143], v[64:79]
	v_add_u32_e32 v238, s15, v175
	ds_read_b128 v[246:249], v238 offset:49152
	ds_read_b128 v[238:241], v238 offset:57344
	s_add_i32 m0, s86, 0xc000
	s_nop 0
	global_load_lds_dwordx4 v154, s[40:41]
	v_add_f32_e32 v162, 0, v179
	v_add_f32_e32 v162, v170, v162
	v_add_f32_e32 v162, v172, v162
	v_add_f32_e32 v162, v174, v162
	s_waitcnt lgkmcnt(2)
	v_mfma_f32_32x32x16_bf16 v[96:111], v[224:227], v[136:139], v[96:111]
	v_mfma_f32_32x32x16_bf16 v[80:95], v[228:231], v[136:139], v[80:95]
	v_add_u32_e32 v228, s15, v173
	ds_read_b128 v[224:227], v228 offset:49152
	ds_read_b128 v[228:231], v228 offset:57344
	v_add_f32_e32 v162, v184, v162
	v_add_f32_e32 v162, v186, v162
	v_add_f32_e32 v162, v188, v162
	v_add_f32_e32 v162, v190, v162
	s_waitcnt lgkmcnt(2)
	v_mfma_f32_32x32x16_bf16 v[96:111], v[246:249], v[132:135], v[96:111]
	v_mfma_f32_32x32x16_bf16 v[80:95], v[238:241], v[132:135], v[80:95]
	v_add_u32_e32 v238, s15, v171
	ds_read_b128 v[246:249], v238 offset:49152
	ds_read_b128 v[238:241], v238 offset:57344
	s_add_i32 m0, s86, 0xc400
	s_nop 0
	global_load_lds_dwordx4 v152, s[40:41]
	s_add_u32 s40, s40, 0x8000
	s_addc_u32 s41, s41, 0
	v_add_f32_e32 v162, v206, v162
	v_add_f32_e32 v162, v200, v162
	v_add_f32_e32 v162, v202, v162
	v_add_f32_e32 v162, v204, v162
	s_waitcnt lgkmcnt(2)
	v_mfma_f32_32x32x16_bf16 v[96:111], v[224:227], v[128:131], v[96:111]
	v_mfma_f32_32x32x16_bf16 v[80:95], v[228:231], v[128:131], v[80:95]
	v_add_u32_e32 v228, s15, v169
	ds_read_b128 v[224:227], v228 offset:49152
	ds_read_b128 v[228:231], v228 offset:57344
	v_add_f32_e32 v162, v216, v162
	v_add_f32_e32 v162, v218, v162
	v_add_f32_e32 v162, v220, v162
	v_add_f32_e32 v162, v222, v162
	s_waitcnt lgkmcnt(2)
	v_mfma_f32_32x32x16_bf16 v[96:111], v[246:249], v[124:127], v[96:111]
	v_mfma_f32_32x32x16_bf16 v[80:95], v[238:241], v[124:127], v[80:95]
	v_add_u32_e32 v238, s15, v167
	ds_read_b128 v[246:249], v238 offset:49152
	ds_read_b128 v[238:241], v238 offset:57344
	s_mov_b32 m0, s87
	s_nop 0
	global_load_lds_dwordx4 v150, s[84:85]
	v_add_f32_e32 v162, v168, v162
	v_add_f32_e32 v162, v156, v162
	v_add_f32_e32 v162, v158, v162
	v_add_f32_e32 v162, v166, v162
	s_waitcnt lgkmcnt(2)
	v_mfma_f32_32x32x16_bf16 v[96:111], v[224:227], v[120:123], v[96:111]
	v_mfma_f32_32x32x16_bf16 v[80:95], v[228:231], v[120:123], v[80:95]
	v_add_u32_e32 v228, s15, v159
	ds_read_b128 v[224:227], v228 offset:49152
	ds_read_b128 v[228:231], v228 offset:57344
	v_add_f32_e32 v162, v176, v162
	v_add_f32_e32 v162, v178, v162
	v_add_f32_e32 v162, v180, v162
	v_add_f32_e32 v162, v182, v162
	s_waitcnt lgkmcnt(2)
	v_mfma_f32_32x32x16_bf16 v[96:111], v[246:249], v[116:119], v[96:111]
	v_mfma_f32_32x32x16_bf16 v[80:95], v[238:241], v[116:119], v[80:95]
	s_add_i32 m0, s87, 0x400
	s_nop 0
	global_load_lds_dwordx4 v148, s[84:85]
	s_add_u32 s84, s84, 0x8000
	s_addc_u32 s85, s85, 0
	v_add_f32_e32 v162, v198, v162
	v_add_f32_e32 v162, v196, v162
	v_add_f32_e32 v162, v192, v162
	s_waitcnt lgkmcnt(0)
	v_mfma_f32_32x32x16_bf16 v[96:111], v[224:227], v[112:115], v[96:111]
	v_cvt_pk_bf16_f32 v238, v179, v170
	v_cvt_pk_bf16_f32 v179, v192, v194
	v_add_f32_e32 v162, v194, v162
	v_cvt_pk_bf16_f32 v241, v188, v190
	v_cvt_pk_bf16_f32 v190, v176, v178
	v_cvt_pk_bf16_f32 v178, v198, v196
	v_mfma_f32_32x32x16_bf16 v[80:95], v[228:231], v[112:115], v[80:95]
	s_bitcmp1_b32 s47, 1
	s_cselect_b32 s17, 0, 0x8000
	v_add_u32_e32 v246, s17, v147
	ds_read_b64_tr_b16 v[192:193], v246 offset:0
	ds_read_b64_tr_b16 v[194:195], v246 offset:0x100
	ds_read_b64_tr_b16 v[196:197], v246 offset:0x1000
	ds_read_b64_tr_b16 v[198:199], v246 offset:0x1100
	v_cvt_pk_bf16_f32 v240, v184, v186
	v_cvt_pk_bf16_f32 v184, v206, v200
	ds_read_b64_tr_b16 v[200:201], v246 offset:0x2000
	ds_read_b64_tr_b16 v[202:203], v246 offset:0x2100
	ds_read_b64_tr_b16 v[204:205], v246 offset:0x3000
	ds_read_b64_tr_b16 v[206:207], v246 offset:0x3100
	v_add_f32_e32 v162, v208, v162
	v_cvt_pk_bf16_f32 v180, v208, v210
	ds_read_b64_tr_b16 v[208:209], v246 offset:0x200
	v_add_f32_e32 v162, v210, v162
	ds_read_b64_tr_b16 v[210:211], v246 offset:0x300
	v_add_f32_e32 v162, v212, v162
	ds_read_b64_tr_b16 v[212:213], v246 offset:0x1200
	v_add_f32_e32 v162, v214, v162
	ds_read_b64_tr_b16 v[214:215], v246 offset:0x1300
	v_cvt_pk_bf16_f32 v186, v216, v218
	ds_read_b64_tr_b16 v[216:217], v246 offset:0x2200
	ds_read_b64_tr_b16 v[218:219], v246 offset:0x2300
	ds_read_b64_tr_b16 v[220:221], v246 offset:0x3200
	ds_read_b64_tr_b16 v[222:223], v246 offset:0x3300
	s_waitcnt lgkmcnt(8)
; #define SBAR() __builtin_amdgcn_sched_barrier(0)
; #define PV_RD2(D0, X) const s16x4 X##l0 = tr_read<v_rd_off2(D0, 0, 0)>(vb), X##h0 = tr_read<v_rd_off2(D0, 0, 1)>(vb), X##l1 = tr_read<v_rd_off2(D0, 1, 0)>(vb), X##h1 = tr_read<v_rd_off2(D0, 1, 1)>(vb), \
;                               X##l2 = tr_read<v_rd_off2(D0, 2, 0)>(vb), X##h2 = tr_read<v_rd_off2(D0, 2, 1)>(vb), X##l3 = tr_read<v_rd_off2(D0, 3, 0)>(vb), X##h3 = tr_read<v_rd_off2(D0, 3, 1)>(vb)
; #define EXP4(P, B) do { P[(B) + 0] = __builtin_amdgcn_exp2f(P[(B) + 0]); P[(B) + 1] = __builtin_amdgcn_exp2f(P[(B) + 1]); P[(B) + 2] = __builtin_amdgcn_exp2f(P[(B) + 2]); P[(B) + 3] = __builtin_amdgcn_exp2f(P[(B) + 3]); } while (0)
; #define DWAIT() asm volatile("s_waitcnt vmcnt(0)" ::: "memory")
; #define ROT() do { const int t_ = sP; sP = sC; sC = sN; sN = t_; } while (0)
; __device__ __forceinline__ void pv_d03(f32x16* o, int vb, bf16x8 pa0, bf16x8 pa1, bf16x8 pa2, bf16x8 pa3, f32x16& pn, f32x16& pm) {
;   PV_RD2(0, a);
;   PV_RD2(1, b); asm volatile("s_waitcnt lgkmcnt(8)" ::: "memory"); SBAR(); PV_MM2(o[0], a); EXP4(pn, 0); EXP4(pm, 0); SBAR();
;   PV_RD2(2, c); asm volatile("s_waitcnt lgkmcnt(8)" ::: "memory"); SBAR(); PV_MM2(o[1], b); EXP4(pn, 4); EXP4(pm, 4); SBAR();
;   PV_RD2(3, d); asm volatile("s_waitcnt lgkmcnt(8)" ::: "memory"); SBAR(); PV_MM2(o[2], c); EXP4(pn, 8); EXP4(pm, 8); SBAR();
;   asm volatile("s_waitcnt lgkmcnt(0)" ::: "memory"); SBAR(); PV_MM2(o[3], d); EXP4(pn, 12); EXP4(pm, 12);
; }
; __device__ __forceinline__ void attn_dense_body(const bf16* Qb, const bf16* __restrict__ Kh, const bf16* __restrict__ Vh, const bf16* __restrict__ Zb, ...
;     ...
;     DWAIT(); __syncthreads(); ROT();
;     SDMA(sN, (j + 2) * KVBLK);
;     SBAR(); qkt3(pA0, pA1, KSLOT(sC), qr, r32, hi, cinit);
;     finishSM4<16>(pB0, pB1, l_reg, pa0, pa1, pa2, pa3);
;     pv_d03(o, vb0 + sP * (int)SHM_V, pa0, pa1, pa2, pa3, pA0, pA1);
	v_add_f32_e32 v146, v146, v162
	v_cvt_pk_bf16_f32 v188, v168, v156
	v_cvt_pk_bf16_f32 v239, v172, v174
	s_nop 1
	v_mfma_f32_32x32x16_bf16 v[48:63], v[192:195], v[238:241], v[48:63]
	v_exp_f32_e32 v156, v96
	v_exp_f32_e32 v158, v97
	v_exp_f32_e32 v166, v82
	v_exp_f32_e32 v168, v83
	v_exp_f32_e32 v162, v98
	v_exp_f32_e32 v163, v99
	v_exp_f32_e32 v164, v80
	v_mfma_f32_32x32x16_bf16 v[48:63], v[196:199], v[184:187], v[48:63]
	v_exp_f32_e32 v165, v81
	v_mfma_f32_32x32x16_bf16 v[48:63], v[200:203], v[188:191], v[48:63]
	v_mfma_f32_32x32x16_bf16 v[48:63], v[204:207], v[178:181], v[48:63]
	ds_read_b64_tr_b16 v[80:81], v246 offset:0x400
	ds_read_b64_tr_b16 v[82:83], v246 offset:0x500
	ds_read_b64_tr_b16 v[96:97], v246 offset:0x1400
	ds_read_b64_tr_b16 v[98:99], v246 offset:0x1500
	ds_read_b64_tr_b16 v[192:193], v246 offset:0x2400
	ds_read_b64_tr_b16 v[194:195], v246 offset:0x2500
	ds_read_b64_tr_b16 v[196:197], v246 offset:0x3400
	ds_read_b64_tr_b16 v[198:199], v246 offset:0x3500
	s_waitcnt lgkmcnt(8)
	v_mfma_f32_32x32x16_bf16 v[32:47], v[208:211], v[238:241], v[32:47]
	v_exp_f32_e32 v170, v100
	v_exp_f32_e32 v172, v101
	v_exp_f32_e32 v174, v102
	v_exp_f32_e32 v176, v103
	v_mfma_f32_32x32x16_bf16 v[32:47], v[212:215], v[184:187], v[32:47]
	v_mfma_f32_32x32x16_bf16 v[32:47], v[216:219], v[188:191], v[32:47]
	v_exp_f32_e32 v216, v84
	v_exp_f32_e32 v218, v86
	v_exp_f32_e32 v217, v85
	v_exp_f32_e32 v219, v87
	v_mfma_f32_32x32x16_bf16 v[32:47], v[220:223], v[178:181], v[32:47]
	ds_read_b64_tr_b16 v[84:85], v246 offset:0x600
	ds_read_b64_tr_b16 v[86:87], v246 offset:0x700
	ds_read_b64_tr_b16 v[100:101], v246 offset:0x1600
	ds_read_b64_tr_b16 v[102:103], v246 offset:0x1700
	ds_read_b64_tr_b16 v[200:201], v246 offset:0x2600
	ds_read_b64_tr_b16 v[202:203], v246 offset:0x2700
	ds_read_b64_tr_b16 v[204:205], v246 offset:0x3600
	ds_read_b64_tr_b16 v[206:207], v246 offset:0x3700
	s_waitcnt lgkmcnt(8)
	v_mfma_f32_32x32x16_bf16 v[16:31], v[80:83], v[238:241], v[16:31]
	v_exp_f32_e32 v220, v88
	v_exp_f32_e32 v222, v90
	v_exp_f32_e32 v221, v89
	v_exp_f32_e32 v223, v91
	v_mfma_f32_32x32x16_bf16 v[16:31], v[96:99], v[184:187], v[16:31]
	v_mfma_f32_32x32x16_bf16 v[16:31], v[192:195], v[188:191], v[16:31]
	v_exp_f32_e32 v192, v104
	v_exp_f32_e32 v194, v106
	v_exp_f32_e32 v193, v105
	v_exp_f32_e32 v195, v107
	v_mfma_f32_32x32x16_bf16 v[16:31], v[196:199], v[178:181], v[16:31]
	s_waitcnt lgkmcnt(0)
	s_waitcnt vmcnt(0)
	s_barrier
	s_add_i32 s86, s90, s14
	s_mov_b32 s87, 0x4000
	s_bitcmp1_b32 s47, 1
	s_cselect_b32 s87, 0x18000, s87
	s_add_i32 s87, s87, s90
	v_mfma_f32_32x32x16_bf16 v[0:15], v[84:87], v[238:241], v[0:15]
	v_exp_f32_e32 v196, v94
	v_mfma_f32_32x32x16_bf16 v[0:15], v[100:103], v[184:187], v[0:15]
	v_exp_f32_e32 v186, v108
	v_exp_f32_e32 v187, v109
	v_exp_f32_e32 v197, v95
	v_mfma_f32_32x32x16_bf16 v[0:15], v[200:203], v[188:191], v[0:15]
	v_exp_f32_e32 v188, v110
	v_exp_f32_e32 v190, v92
	v_exp_f32_e32 v189, v111
	v_exp_f32_e32 v191, v93
	v_mfma_f32_32x32x16_bf16 v[0:15], v[204:207], v[178:181], v[0:15]
	s_add_i32 s16, s49, 0
	v_add_u32_e32 v182, s16, v157
	ds_read_b128 v[178:181], v182 offset:49152
	ds_read_b128 v[182:185], v182 offset:57344
	v_add_u32_e32 v246, s16, v177
	ds_read_b128 v[238:241], v246 offset:49152
	ds_read_b128 v[246:249], v246 offset:57344
	s_mov_b32 s17, 0x18000
	s_bitcmp1_b32 s47, 1
	s_cselect_b32 s17, 0x4000, s17
	v_add_u32_e32 v206, s17, v147
	v_cvt_pk_bf16_f32 v214, v186, v187
	v_cvt_pk_bf16_f32 v215, v188, v189
	v_cvt_pk_bf16_f32 v230, v190, v191
	v_cvt_pk_bf16_f32 v212, v192, v193
	s_waitcnt lgkmcnt(2)
	v_mfma_f32_32x32x16_bf16 v[96:111], v[178:181], v[140:143], v[64:79]
	v_mfma_f32_32x32x16_bf16 v[80:95], v[182:185], v[140:143], v[64:79]
	v_add_u32_e32 v182, s16, v175
	ds_read_b128 v[178:181], v182 offset:49152
	ds_read_b128 v[182:185], v182 offset:57344
	s_add_i32 m0, s86, 0xc000
	s_nop 0
	global_load_lds_dwordx4 v154, s[40:41]
	v_cvt_pk_bf16_f32 v213, v194, v195
	v_cvt_pk_bf16_f32 v231, v196, v197
	v_cvt_pk_bf16_f32 v226, v216, v217
	s_waitcnt lgkmcnt(2)
	v_mfma_f32_32x32x16_bf16 v[96:111], v[238:241], v[136:139], v[96:111]
	v_mfma_f32_32x32x16_bf16 v[80:95], v[246:249], v[136:139], v[80:95]
	v_add_u32_e32 v246, s16, v173
	ds_read_b128 v[238:241], v246 offset:49152
	ds_read_b128 v[246:249], v246 offset:57344
	v_cvt_pk_bf16_f32 v227, v218, v219
	v_cvt_pk_bf16_f32 v208, v156, v158
	v_cvt_pk_bf16_f32 v210, v170, v172
	s_waitcnt lgkmcnt(2)
	v_mfma_f32_32x32x16_bf16 v[96:111], v[178:181], v[132:135], v[96:111]
	v_mfma_f32_32x32x16_bf16 v[80:95], v[182:185], v[132:135], v[80:95]
	v_add_u32_e32 v182, s16, v171
	ds_read_b128 v[178:181], v182 offset:49152
	ds_read_b128 v[182:185], v182 offset:57344
	s_add_i32 m0, s86, 0xc400
	s_nop 0
	global_load_lds_dwordx4 v152, s[40:41]
	s_add_u32 s40, s40, 0x8000
	s_addc_u32 s41, s41, 0
	v_cvt_pk_bf16_f32 v209, v162, v163
	v_cvt_pk_bf16_f32 v211, v174, v176
	v_cvt_pk_bf16_f32 v224, v164, v165
	s_waitcnt lgkmcnt(2)
	v_mfma_f32_32x32x16_bf16 v[96:111], v[238:241], v[128:131], v[96:111]
	v_mfma_f32_32x32x16_bf16 v[80:95], v[246:249], v[128:131], v[80:95]
	v_add_u32_e32 v246, s16, v169
	ds_read_b128 v[238:241], v246 offset:49152
	ds_read_b128 v[246:249], v246 offset:57344
	v_cvt_pk_bf16_f32 v225, v166, v168
	v_cvt_pk_bf16_f32 v228, v220, v221
	v_cvt_pk_bf16_f32 v229, v222, v223
	s_waitcnt lgkmcnt(2)
	v_mfma_f32_32x32x16_bf16 v[96:111], v[178:181], v[124:127], v[96:111]
	v_mfma_f32_32x32x16_bf16 v[80:95], v[182:185], v[124:127], v[80:95]
	v_add_u32_e32 v182, s16, v167
	ds_read_b128 v[178:181], v182 offset:49152
	ds_read_b128 v[182:185], v182 offset:57344
	s_mov_b32 m0, s87
	s_nop 0
	global_load_lds_dwordx4 v150, s[84:85]
	s_waitcnt lgkmcnt(2)
; #define SBAR() __builtin_amdgcn_sched_barrier(0)
; #define PK8(P, BASE, OUT) do { u32x4 w = {cvtpk(P[BASE + 0], P[BASE + 1]), cvtpk(P[BASE + 2], P[BASE + 3]), cvtpk(P[BASE + 4], P[BASE + 5]), cvtpk(P[BASE + 6], P[BASE + 7])}; OUT = *reinterpret_cast<bf16x8*>(&w); } while (0)
; #define PV_RD2(D0, X) const s16x4 X##l0 = tr_read<v_rd_off2(D0, 0, 0)>(vb), X##h0 = tr_read<v_rd_off2(D0, 0, 1)>(vb), X##l1 = tr_read<v_rd_off2(D0, 1, 0)>(vb), X##h1 = tr_read<v_rd_off2(D0, 1, 1)>(vb), \
;                               X##l2 = tr_read<v_rd_off2(D0, 2, 0)>(vb), X##h2 = tr_read<v_rd_off2(D0, 2, 1)>(vb), X##l3 = tr_read<v_rd_off2(D0, 3, 0)>(vb), X##h3 = tr_read<v_rd_off2(D0, 3, 1)>(vb)
; #define EXP4(P, B) do { P[(B) + 0] = __builtin_amdgcn_exp2f(P[(B) + 0]); P[(B) + 1] = __builtin_amdgcn_exp2f(P[(B) + 1]); P[(B) + 2] = __builtin_amdgcn_exp2f(P[(B) + 2]); P[(B) + 3] = __builtin_amdgcn_exp2f(P[(B) + 3]); } while (0)
; template <int FIRST> __device__ __forceinline__ void finishSM4(f32x16& p0, f32x16& p1, float& l_reg, bf16x8& pa0, bf16x8& pa1, bf16x8& pa2, bf16x8& pa3) {
;   for (int r = FIRST; r < 16; ++r) p1[r] = __builtin_amdgcn_exp2f(p1[r]);
;   float ps = 0; for (int r = 0; r < 16; ++r) ps += p0[r]; for (int r = 0; r < 16; ++r) ps += p1[r];
;   l_reg += ps;
;     ...
;   PK8(p0, 0, pa0); PK8(p0, 8, pa1); PK8(p1, 0, pa2); PK8(p1, 8, pa3);
;     ...
; }
; __device__ __forceinline__ void pv_d03(f32x16* o, int vb, bf16x8 pa0, bf16x8 pa1, bf16x8 pa2, bf16x8 pa3, f32x16& pn, f32x16& pm) {
;   PV_RD2(0, a);
;   PV_RD2(1, b); asm volatile("s_waitcnt lgkmcnt(8)" ::: "memory"); SBAR(); PV_MM2(o[0], a); EXP4(pn, 0); EXP4(pm, 0); SBAR();
;   PV_RD2(2, c); asm volatile("s_waitcnt lgkmcnt(8)" ::: "memory"); SBAR(); PV_MM2(o[1], b); EXP4(pn, 4); EXP4(pm, 4); SBAR();
;   PV_RD2(3, d); asm volatile("s_waitcnt lgkmcnt(8)" ::: "memory"); SBAR(); PV_MM2(o[2], c); EXP4(pn, 8); EXP4(pm, 8); SBAR();
;   asm volatile("s_waitcnt lgkmcnt(0)" ::: "memory"); SBAR(); PV_MM2(o[3], d); EXP4(pn, 12); EXP4(pm, 12);
; }
	v_mfma_f32_32x32x16_bf16 v[96:111], v[238:241], v[120:123], v[96:111]
	v_mfma_f32_32x32x16_bf16 v[80:95], v[246:249], v[120:123], v[80:95]
	v_add_u32_e32 v246, s16, v159
	ds_read_b128 v[238:241], v246 offset:49152
	ds_read_b128 v[246:249], v246 offset:57344
	s_waitcnt lgkmcnt(2)
	v_mfma_f32_32x32x16_bf16 v[96:111], v[178:181], v[116:119], v[96:111]
	v_mfma_f32_32x32x16_bf16 v[80:95], v[182:185], v[116:119], v[80:95]
	s_add_i32 m0, s87, 0x400
	s_nop 0
	global_load_lds_dwordx4 v148, s[84:85]
	s_add_u32 s84, s84, 0x8000
	s_addc_u32 s85, s85, 0
	v_add_f32_e32 v178, 0, v156
	v_add_f32_e32 v178, v158, v178
	v_add_f32_e32 v178, v162, v178
	v_add_f32_e32 v178, v163, v178
	v_add_f32_e32 v178, v170, v178
	v_add_f32_e32 v178, v172, v178
	v_add_f32_e32 v178, v174, v178
	v_add_f32_e32 v178, v176, v178
	v_add_f32_e32 v178, v192, v178
	v_add_f32_e32 v178, v193, v178
	v_add_f32_e32 v178, v194, v178
	v_add_f32_e32 v178, v195, v178
	v_add_f32_e32 v178, v186, v178
	v_add_f32_e32 v178, v187, v178
	v_add_f32_e32 v178, v188, v178
	v_add_f32_e32 v178, v189, v178
	s_waitcnt lgkmcnt(0)
	v_mfma_f32_32x32x16_bf16 v[96:111], v[238:241], v[112:115], v[96:111]
	v_add_f32_e32 v178, v164, v178
	v_add_f32_e32 v178, v165, v178
	v_add_f32_e32 v178, v166, v178
	v_add_f32_e32 v178, v168, v178
	v_add_f32_e32 v178, v216, v178
	v_add_f32_e32 v178, v217, v178
	v_add_f32_e32 v178, v218, v178
	v_add_f32_e32 v178, v219, v178
	v_add_f32_e32 v178, v220, v178
	v_add_f32_e32 v178, v221, v178
	v_add_f32_e32 v178, v222, v178
	v_add_f32_e32 v178, v223, v178
	v_add_f32_e32 v178, v190, v178
	v_add_f32_e32 v178, v191, v178
	v_add_f32_e32 v178, v196, v178
	v_add_f32_e32 v178, v197, v178
	v_add_f32_e32 v146, v146, v178
	ds_read_b64_tr_b16 v[178:179], v206 offset:0
	ds_read_b64_tr_b16 v[180:181], v206 offset:0x100
	v_mfma_f32_32x32x16_bf16 v[80:95], v[246:249], v[112:115], v[80:95]
	ds_read_b64_tr_b16 v[182:183], v206 offset:0x1000
	ds_read_b64_tr_b16 v[184:185], v206 offset:0x1100
	ds_read_b64_tr_b16 v[186:187], v206 offset:0x2000
	ds_read_b64_tr_b16 v[188:189], v206 offset:0x2100
	ds_read_b64_tr_b16 v[190:191], v206 offset:0x3000
	ds_read_b64_tr_b16 v[192:193], v206 offset:0x3100
	ds_read_b64_tr_b16 v[194:195], v206 offset:0x200
	ds_read_b64_tr_b16 v[196:197], v206 offset:0x300
	ds_read_b64_tr_b16 v[198:199], v206 offset:0x1200
	ds_read_b64_tr_b16 v[200:201], v206 offset:0x1300
	ds_read_b64_tr_b16 v[202:203], v206 offset:0x2200
	ds_read_b64_tr_b16 v[204:205], v206 offset:0x2300
	ds_read_b64_tr_b16 v[216:217], v206 offset:0x3200
	ds_read_b64_tr_b16 v[218:219], v206 offset:0x3300
	s_waitcnt lgkmcnt(8)
	v_mfma_f32_32x32x16_bf16 v[48:63], v[178:181], v[208:211], v[48:63]
	v_exp_f32_e32 v179, v96
	v_exp_f32_e32 v170, v97
	v_exp_f32_e32 v172, v98
	v_exp_f32_e32 v174, v99
	v_exp_f32_e32 v168, v80
	v_exp_f32_e32 v156, v81
	v_exp_f32_e32 v158, v82
	v_mfma_f32_32x32x16_bf16 v[48:63], v[182:185], v[212:215], v[48:63]
	v_exp_f32_e32 v166, v83
	v_mfma_f32_32x32x16_bf16 v[48:63], v[186:189], v[224:227], v[48:63]
	v_mfma_f32_32x32x16_bf16 v[48:63], v[190:193], v[228:231], v[48:63]
	ds_read_b64_tr_b16 v[80:81], v206 offset:0x400
	ds_read_b64_tr_b16 v[82:83], v206 offset:0x500
	ds_read_b64_tr_b16 v[96:97], v206 offset:0x1400
	ds_read_b64_tr_b16 v[98:99], v206 offset:0x1500
	ds_read_b64_tr_b16 v[220:221], v206 offset:0x2400
	ds_read_b64_tr_b16 v[222:223], v206 offset:0x2500
	ds_read_b64_tr_b16 v[238:239], v206 offset:0x3400
	ds_read_b64_tr_b16 v[240:241], v206 offset:0x3500
	s_waitcnt lgkmcnt(8)
	v_mfma_f32_32x32x16_bf16 v[32:47], v[194:197], v[208:211], v[32:47]
	v_exp_f32_e32 v184, v100
	v_exp_f32_e32 v186, v101
	v_exp_f32_e32 v188, v102
	v_exp_f32_e32 v190, v103
	v_exp_f32_e32 v176, v84
	v_exp_f32_e32 v178, v85
	v_exp_f32_e32 v180, v86
	v_mfma_f32_32x32x16_bf16 v[32:47], v[198:201], v[212:215], v[32:47]
	v_exp_f32_e32 v182, v87
	v_mfma_f32_32x32x16_bf16 v[32:47], v[202:205], v[224:227], v[32:47]
	v_mfma_f32_32x32x16_bf16 v[32:47], v[216:219], v[228:231], v[32:47]
	ds_read_b64_tr_b16 v[84:85], v206 offset:0x600
	ds_read_b64_tr_b16 v[86:87], v206 offset:0x700
	ds_read_b64_tr_b16 v[100:101], v206 offset:0x1600
	ds_read_b64_tr_b16 v[102:103], v206 offset:0x1700
	ds_read_b64_tr_b16 v[248:249], v206 offset:0x2600
	ds_read_b64_tr_b16 v[250:251], v206 offset:0x2700
	ds_read_b64_tr_b16 v[162:163], v206 offset:0x3600
	ds_read_b64_tr_b16 v[164:165], v206 offset:0x3700
	s_waitcnt lgkmcnt(8)
	v_mfma_f32_32x32x16_bf16 v[16:31], v[80:83], v[208:211], v[16:31]
	v_exp_f32_e32 v206, v104
	v_exp_f32_e32 v200, v105
	v_exp_f32_e32 v202, v106
	v_exp_f32_e32 v204, v107
	v_exp_f32_e32 v198, v88
	v_exp_f32_e32 v196, v89
	v_exp_f32_e32 v192, v90
	v_mfma_f32_32x32x16_bf16 v[16:31], v[96:99], v[212:215], v[16:31]
	v_exp_f32_e32 v194, v91
	v_mfma_f32_32x32x16_bf16 v[16:31], v[220:223], v[224:227], v[16:31]
	v_mfma_f32_32x32x16_bf16 v[16:31], v[238:241], v[228:231], v[16:31]
	s_waitcnt lgkmcnt(0)
	v_mfma_f32_32x32x16_bf16 v[0:15], v[84:87], v[208:211], v[0:15]
	v_exp_f32_e32 v216, v108
	v_exp_f32_e32 v218, v109
	v_exp_f32_e32 v220, v110
	v_exp_f32_e32 v222, v111
	v_exp_f32_e32 v208, v92
	v_exp_f32_e32 v210, v93
	v_mfma_f32_32x32x16_bf16 v[0:15], v[100:103], v[212:215], v[0:15]
	v_exp_f32_e32 v212, v94
	v_exp_f32_e32 v214, v95
	s_add_i32 s47, s47, 2
	s_mov_b32 s54, s48
	s_mov_b32 s48, s53
	v_mfma_f32_32x32x16_bf16 v[0:15], v[248:251], v[224:227], v[0:15]
	s_waitcnt vmcnt(0)
	s_barrier
	s_cmp_lt_u32 s47, s52
	v_mfma_f32_32x32x16_bf16 v[0:15], v[162:165], v[228:231], v[0:15]
	s_cbranch_scc1 .LBB0_117
; #define SBAR() __builtin_amdgcn_sched_barrier(0)
; #define PV_RD2(D0, X) const s16x4 X##l0 = tr_read<v_rd_off2(D0, 0, 0)>(vb), X##h0 = tr_read<v_rd_off2(D0, 0, 1)>(vb), X##l1 = tr_read<v_rd_off2(D0, 1, 0)>(vb), X##h1 = tr_read<v_rd_off2(D0, 1, 1)>(vb), \
;                               X##l2 = tr_read<v_rd_off2(D0, 2, 0)>(vb), X##h2 = tr_read<v_rd_off2(D0, 2, 1)>(vb), X##l3 = tr_read<v_rd_off2(D0, 3, 0)>(vb), X##h3 = tr_read<v_rd_off2(D0, 3, 1)>(vb)
; #define EXP4(P, B) do { P[(B) + 0] = __builtin_amdgcn_exp2f(P[(B) + 0]); P[(B) + 1] = __builtin_amdgcn_exp2f(P[(B) + 1]); P[(B) + 2] = __builtin_amdgcn_exp2f(P[(B) + 2]); P[(B) + 3] = __builtin_amdgcn_exp2f(P[(B) + 3]); } while (0)
; __device__ __forceinline__ void pv_d03(f32x16* o, int vb, bf16x8 pa0, bf16x8 pa1, bf16x8 pa2, bf16x8 pa3, f32x16& pn, f32x16& pm) {
;   PV_RD2(0, a);
;   PV_RD2(1, b); asm volatile("s_waitcnt lgkmcnt(8)" ::: "memory"); SBAR(); PV_MM2(o[0], a); EXP4(pn, 0); EXP4(pm, 0); SBAR();
;   PV_RD2(2, c); asm volatile("s_waitcnt lgkmcnt(8)" ::: "memory"); SBAR(); PV_MM2(o[1], b); EXP4(pn, 4); EXP4(pm, 4); SBAR();
;   PV_RD2(3, d); asm volatile("s_waitcnt lgkmcnt(8)" ::: "memory"); SBAR(); PV_MM2(o[2], c); EXP4(pn, 8); EXP4(pm, 8); SBAR();
; __device__ __forceinline__ void attn_dense_body(const bf16* Qb, const bf16* __restrict__ Kh, const bf16* __restrict__ Vh, const bf16* __restrict__ Zb, ...
;     ...
;   SBAR(); qkt3(pB0, pB1, KSLOT(sC), qr, r32, hi, cinit);
;   finishSM4<16>(pA0, pA1, l_reg, pa0, pa1, pa2, pa3); SBAR();
;   pv_d03(o, vb0 + sP * (int)SHM_V, pa0, pa1, pa2, pa3, pB0, pB1);
	s_add_u32 s40, s36, s44
	s_addc_u32 s41, s50, s45
	s_add_i32 s14, s14, 0
	v_add_u32_e32 v100, s14, v157
	ds_read_b128 v[96:99], v100 offset:49152
	v_add_u32_e32 v104, s14, v159
	v_add_f32_e32 v148, 0, v179
	v_cvt_pk_bf16_f32 v108, v179, v170
	v_cvt_pk_bf16_f32 v109, v172, v174
	v_cvt_pk_bf16_f32 v110, v184, v186
	v_cvt_pk_bf16_f32 v111, v188, v190
	s_waitcnt lgkmcnt(0)
	v_mfma_f32_32x32x16_bf16 v[80:95], v[96:99], v[140:143], v[64:79]
	ds_read_b128 v[96:99], v100 offset:57344
	v_add_u32_e32 v100, s14, v177
	s_waitcnt lgkmcnt(0)
	v_mfma_f32_32x32x16_bf16 v[64:79], v[96:99], v[140:143], v[64:79]
	ds_read_b128 v[96:99], v100 offset:49152
	s_waitcnt lgkmcnt(0)
	v_mfma_f32_32x32x16_bf16 v[80:95], v[96:99], v[136:139], v[80:95]
	ds_read_b128 v[96:99], v100 offset:57344
	v_add_u32_e32 v100, s14, v175
	s_waitcnt lgkmcnt(0)
	v_mfma_f32_32x32x16_bf16 v[64:79], v[96:99], v[136:139], v[64:79]
	ds_read_b128 v[96:99], v100 offset:49152
	s_waitcnt lgkmcnt(0)
	v_mfma_f32_32x32x16_bf16 v[80:95], v[96:99], v[132:135], v[80:95]
	ds_read_b128 v[96:99], v100 offset:57344
	v_add_u32_e32 v100, s14, v173
	s_waitcnt lgkmcnt(0)
	v_mfma_f32_32x32x16_bf16 v[64:79], v[96:99], v[132:135], v[64:79]
	ds_read_b128 v[96:99], v100 offset:49152
	s_waitcnt lgkmcnt(0)
	v_mfma_f32_32x32x16_bf16 v[80:95], v[96:99], v[128:131], v[80:95]
	ds_read_b128 v[96:99], v100 offset:57344
	v_add_u32_e32 v100, s14, v171
	s_waitcnt lgkmcnt(0)
	v_mfma_f32_32x32x16_bf16 v[64:79], v[96:99], v[128:131], v[64:79]
	ds_read_b128 v[96:99], v100 offset:49152
	s_waitcnt lgkmcnt(0)
	v_mfma_f32_32x32x16_bf16 v[80:95], v[96:99], v[124:127], v[80:95]
	ds_read_b128 v[96:99], v100 offset:57344
	v_add_u32_e32 v100, s14, v169
	s_waitcnt lgkmcnt(0)
	v_mfma_f32_32x32x16_bf16 v[64:79], v[96:99], v[124:127], v[64:79]
	ds_read_b128 v[96:99], v100 offset:49152
	s_waitcnt lgkmcnt(0)
	v_mfma_f32_32x32x16_bf16 v[80:95], v[96:99], v[120:123], v[80:95]
	ds_read_b128 v[96:99], v100 offset:57344
	v_add_u32_e32 v100, s14, v167
	s_waitcnt lgkmcnt(0)
	v_mfma_f32_32x32x16_bf16 v[64:79], v[96:99], v[120:123], v[64:79]
	ds_read_b128 v[96:99], v100 offset:49152
	s_waitcnt lgkmcnt(0)
	v_mfma_f32_32x32x16_bf16 v[80:95], v[96:99], v[116:119], v[80:95]
	ds_read_b128 v[96:99], v100 offset:57344
	ds_read_b128 v[100:103], v104 offset:49152
	ds_read_b128 v[104:107], v104 offset:57344
	s_waitcnt lgkmcnt(2)
	v_mfma_f32_32x32x16_bf16 v[64:79], v[96:99], v[116:119], v[64:79]
	v_cvt_pk_bf16_f32 v96, v206, v200
	v_cvt_pk_bf16_f32 v97, v202, v204
	v_cvt_pk_bf16_f32 v98, v216, v218
	v_cvt_pk_bf16_f32 v99, v220, v222
	v_cvt_pk_bf16_f32 v116, v198, v196
	v_cvt_pk_bf16_f32 v117, v192, v194
	v_cvt_pk_bf16_f32 v118, v208, v210
	s_waitcnt lgkmcnt(1)
	v_mfma_f32_32x32x16_bf16 v[80:95], v[100:103], v[112:115], v[80:95]
	v_cvt_pk_bf16_f32 v100, v168, v156
	v_cvt_pk_bf16_f32 v101, v158, v166
	v_cvt_pk_bf16_f32 v102, v176, v178
	v_cvt_pk_bf16_f32 v103, v180, v182
	v_cvt_pk_bf16_f32 v119, v212, v214
	s_waitcnt lgkmcnt(0)
	v_mfma_f32_32x32x16_bf16 v[64:79], v[104:107], v[112:115], v[64:79]
	s_mov_b32 s87, 0x18000
	s_bitcmp1_b32 s52, 1
	s_cselect_b32 s87, 0x4000, s87
	v_add_u32_e32 v246, s87, v147
	s_bitcmp1_b32 s52, 1
	s_cselect_b32 s87, 0, 0x8000
	v_add_u32_e32 v147, s87, v147
	ds_read_b64_tr_b16 v[104:105], v147 offset:0
	ds_read_b64_tr_b16 v[106:107], v147 offset:0x100
	ds_read_b64_tr_b16 v[112:113], v147 offset:0x1000
	ds_read_b64_tr_b16 v[114:115], v147 offset:0x1100
	ds_read_b64_tr_b16 v[120:121], v147 offset:0x2000
	ds_read_b64_tr_b16 v[122:123], v147 offset:0x2100
	ds_read_b64_tr_b16 v[124:125], v147 offset:0x3000
	ds_read_b64_tr_b16 v[126:127], v147 offset:0x3100
	ds_read_b64_tr_b16 v[128:129], v147 offset:0x200
	ds_read_b64_tr_b16 v[130:131], v147 offset:0x300
	ds_read_b64_tr_b16 v[132:133], v147 offset:0x1200
	ds_read_b64_tr_b16 v[134:135], v147 offset:0x1300
	ds_read_b64_tr_b16 v[136:137], v147 offset:0x2200
	ds_read_b64_tr_b16 v[138:139], v147 offset:0x2300
	ds_read_b64_tr_b16 v[140:141], v147 offset:0x3200
	ds_read_b64_tr_b16 v[142:143], v147 offset:0x3300
	s_waitcnt lgkmcnt(8)
	s_nop 0
	v_mfma_f32_32x32x16_bf16 v[48:63], v[104:107], v[108:111], v[48:63]
	s_nop 1
	v_exp_f32_e32 v171, v80
	v_exp_f32_e32 v173, v81
	v_exp_f32_e32 v175, v82
	v_exp_f32_e32 v185, v83
	s_nop 2
	v_exp_f32_e32 v157, v64
	v_exp_f32_e32 v159, v65
	v_exp_f32_e32 v167, v66
	v_mfma_f32_32x32x16_bf16 v[48:63], v[112:115], v[96:99], v[48:63]
	v_exp_f32_e32 v177, v67
	v_mfma_f32_32x32x16_bf16 v[48:63], v[120:123], v[100:103], v[48:63]
	v_mfma_f32_32x32x16_bf16 v[48:63], v[124:127], v[116:119], v[48:63]
	ds_read_b64_tr_b16 v[64:65], v147 offset:0x400
	ds_read_b64_tr_b16 v[66:67], v147 offset:0x500
	ds_read_b64_tr_b16 v[80:81], v147 offset:0x1400
	ds_read_b64_tr_b16 v[82:83], v147 offset:0x1500
	ds_read_b64_tr_b16 v[104:105], v147 offset:0x2400
	ds_read_b64_tr_b16 v[106:107], v147 offset:0x2500
	ds_read_b64_tr_b16 v[112:113], v147 offset:0x3400
	ds_read_b64_tr_b16 v[114:115], v147 offset:0x3500
	s_waitcnt lgkmcnt(8)
	v_mfma_f32_32x32x16_bf16 v[32:47], v[128:131], v[108:111], v[32:47]
	v_exp_f32_e32 v187, v84
	v_exp_f32_e32 v189, v85
	v_exp_f32_e32 v191, v86
	v_exp_f32_e32 v207, v87
	v_exp_f32_e32 v179, v68
	v_exp_f32_e32 v181, v69
	v_exp_f32_e32 v183, v70
	v_mfma_f32_32x32x16_bf16 v[32:47], v[132:135], v[96:99], v[32:47]
	v_exp_f32_e32 v199, v71
	v_mfma_f32_32x32x16_bf16 v[32:47], v[136:139], v[100:103], v[32:47]
	v_mfma_f32_32x32x16_bf16 v[32:47], v[140:143], v[116:119], v[32:47]
	ds_read_b64_tr_b16 v[68:69], v147 offset:0x600
	ds_read_b64_tr_b16 v[70:71], v147 offset:0x700
	ds_read_b64_tr_b16 v[84:85], v147 offset:0x1600
	ds_read_b64_tr_b16 v[86:87], v147 offset:0x1700
	ds_read_b64_tr_b16 v[120:121], v147 offset:0x2600
	ds_read_b64_tr_b16 v[122:123], v147 offset:0x2700
	ds_read_b64_tr_b16 v[124:125], v147 offset:0x3600
	ds_read_b64_tr_b16 v[126:127], v147 offset:0x3700
	s_waitcnt lgkmcnt(8)
; #define SBAR() __builtin_amdgcn_sched_barrier(0)
; #define PV_RD2(D0, X) const s16x4 X##l0 = tr_read<v_rd_off2(D0, 0, 0)>(vb), X##h0 = tr_read<v_rd_off2(D0, 0, 1)>(vb), X##l1 = tr_read<v_rd_off2(D0, 1, 0)>(vb), X##h1 = tr_read<v_rd_off2(D0, 1, 1)>(vb), \
;                               X##l2 = tr_read<v_rd_off2(D0, 2, 0)>(vb), X##h2 = tr_read<v_rd_off2(D0, 2, 1)>(vb), X##l3 = tr_read<v_rd_off2(D0, 3, 0)>(vb), X##h3 = tr_read<v_rd_off2(D0, 3, 1)>(vb)
; __device__ __forceinline__ void pv_d02(f32x16* o, int vb, bf16x8 pa0, bf16x8 pa1, bf16x8 pa2, bf16x8 pa3) {
;   PV_RD2(0, a);
;   PV_RD2(1, b); asm volatile("s_waitcnt lgkmcnt(8)" ::: "memory"); SBAR(); PV_MM2(o[0], a); SBAR();
;   PV_RD2(2, c); asm volatile("s_waitcnt lgkmcnt(8)" ::: "memory"); SBAR(); PV_MM2(o[1], b); SBAR();
;   PV_RD2(3, d); asm volatile("s_waitcnt lgkmcnt(8)" ::: "memory"); SBAR(); PV_MM2(o[2], c); SBAR();
;   asm volatile("s_waitcnt lgkmcnt(0)" ::: "memory"); SBAR(); PV_MM2(o[3], d);
; }
; __device__ __forceinline__ void attn_dense_body(const bf16* Qb, const bf16* __restrict__ Kh, const bf16* __restrict__ Vh, const bf16* __restrict__ Zb, ...
;     ...
;   pv_d03(o, vb0 + sP * (int)SHM_V, pa0, pa1, pa2, pa3, pB0, pB1);
;   finishSM4<16>(pB0, pB1, l_reg, pa0, pa1, pa2, pa3); SBAR();
;   pv_d02(o, vb0 + sC * (int)SHM_V, pa0, pa1, pa2, pa3);
;     ...
;   { auto rr = __builtin_amdgcn_permlane32_swap(__float_as_uint(l_reg), __float_as_uint(l_reg), false, false); l_reg = __uint_as_float(rr[0]) + __uint_as_float(rr[1]); }
;   const float rl = __builtin_amdgcn_rcpf(l_reg);
;   { int lb = (wid * QBLK + r32) * LDO + 4 * hi; asm volatile("" : "+v"(lb));
;     unsigned short* Ow = (unsigned short*)Ob + lb; const unsigned short* Zw = (const unsigned short*)Zb + lb;
; #pragma unroll
;     for (int d0 = 0; d0 < 4; ++d0)
; #pragma unroll
;       for (int g = 0; g < 4; ++g) { const int co = d0 * 32 + 8 * g; const unsigned long long zz = *(const unsigned long long*)(Zw + co);
	v_mfma_f32_32x32x16_bf16 v[16:31], v[64:67], v[108:111], v[16:31]
	v_exp_f32_e32 v201, v88
	v_exp_f32_e32 v203, v89
	v_exp_f32_e32 v205, v90
	v_exp_f32_e32 v217, v91
	v_exp_f32_e32 v197, v72
	v_exp_f32_e32 v193, v73
	v_exp_f32_e32 v195, v74
	v_mfma_f32_32x32x16_bf16 v[16:31], v[80:83], v[96:99], v[16:31]
	v_exp_f32_e32 v209, v75
	v_mfma_f32_32x32x16_bf16 v[16:31], v[104:107], v[100:103], v[16:31]
	v_mfma_f32_32x32x16_bf16 v[16:31], v[112:115], v[116:119], v[16:31]
	s_waitcnt lgkmcnt(0)
	v_mov_b32_e32 v149, v161
	v_add_f32_e64 v64, v170, v148
	v_add_f32_e64 v65, v171, v149
	v_mfma_f32_32x32x16_bf16 v[0:15], v[68:71], v[108:111], v[0:15]
	v_add_f32_e64 v64, v172, v64
	v_add_f32_e64 v65, v173, v65
	v_exp_f32_e32 v219, v92
	v_pk_add_f32 v[64:65], v[174:175], v[64:65]
	v_exp_f32_e32 v221, v93
	v_pk_add_f32 v[64:65], v[184:185], v[64:65]
	v_exp_f32_e32 v223, v94
	v_pk_add_f32 v[64:65], v[186:187], v[64:65]
	v_exp_f32_e32 v169, v95
	v_pk_add_f32 v[64:65], v[188:189], v[64:65]
	v_mfma_f32_32x32x16_bf16 v[0:15], v[84:87], v[96:99], v[0:15]
	v_add_f32_e64 v64, v190, v64
	v_add_f32_e64 v65, v191, v65
	v_exp_f32_e32 v211, v76
	v_pk_add_f32 v[64:65], v[206:207], v[64:65]
	v_exp_f32_e32 v213, v77
	v_pk_add_f32 v[64:65], v[200:201], v[64:65]
	v_exp_f32_e32 v215, v78
	v_pk_add_f32 v[64:65], v[202:203], v[64:65]
	v_mfma_f32_32x32x16_bf16 v[0:15], v[120:123], v[100:103], v[0:15]
	v_add_f32_e64 v64, v204, v64
	v_add_f32_e64 v65, v205, v65
	v_exp_f32_e32 v147, v79
	v_pk_add_f32 v[64:65], v[216:217], v[64:65]
	v_cvt_pk_bf16_f32 v66, v187, v189
	v_pk_add_f32 v[64:65], v[218:219], v[64:65]
	v_cvt_pk_bf16_f32 v67, v191, v207
	v_pk_add_f32 v[64:65], v[220:221], v[64:65]
	v_mfma_f32_32x32x16_bf16 v[0:15], v[124:127], v[116:119], v[0:15]
	v_add_f32_e64 v64, v222, v64
	v_add_f32_e64 v65, v223, v65
	v_cvt_pk_bf16_f32 v68, v201, v203
	v_add_f32_e64 v64, v168, v64
	v_add_f32_e64 v65, v169, v65
	v_cvt_pk_bf16_f32 v69, v205, v217
	v_pk_add_f32 v[64:65], v[156:157], v[64:65]
	v_cvt_pk_bf16_f32 v70, v219, v221
	v_pk_add_f32 v[64:65], v[158:159], v[64:65]
	v_cvt_pk_bf16_f32 v71, v223, v169
	v_pk_add_f32 v[64:65], v[166:167], v[64:65]
	v_cvt_pk_bf16_f32 v72, v157, v159
	v_pk_add_f32 v[64:65], v[176:177], v[64:65]
	v_cvt_pk_bf16_f32 v73, v167, v177
	v_pk_add_f32 v[64:65], v[178:179], v[64:65]
	v_cvt_pk_bf16_f32 v74, v179, v181
	v_pk_add_f32 v[64:65], v[180:181], v[64:65]
	v_cvt_pk_bf16_f32 v75, v183, v199
	v_pk_add_f32 v[64:65], v[182:183], v[64:65]
	v_cvt_pk_bf16_f32 v76, v197, v193
	v_pk_add_f32 v[64:65], v[198:199], v[64:65]
	v_cvt_pk_bf16_f32 v77, v195, v209
	v_pk_add_f32 v[64:65], v[196:197], v[64:65]
	v_cvt_pk_bf16_f32 v78, v211, v213
	v_pk_add_f32 v[64:65], v[192:193], v[64:65]
	v_cvt_pk_bf16_f32 v79, v215, v147
	v_pk_add_f32 v[64:65], v[194:195], v[64:65]
	s_nop 0
	v_pk_add_f32 v[64:65], v[208:209], v[64:65]
	s_nop 0
	v_pk_add_f32 v[64:65], v[210:211], v[64:65]
	s_nop 0
	v_pk_add_f32 v[64:65], v[212:213], v[64:65]
	s_nop 0
	v_pk_add_f32 v[64:65], v[214:215], v[64:65]
	s_nop 0
	v_pk_add_f32 v[64:65], v[146:147], v[64:65]
	s_nop 0
	v_pk_add_f32 v[112:113], v[64:65], v[64:65] op_sel:[0,1] op_sel_hi:[1,0]
	v_cvt_pk_bf16_f32 v64, v171, v173
	v_cvt_pk_bf16_f32 v65, v175, v185
	v_lshlrev_b32_e32 v222, 2, v245
	v_lshl_add_u32 v222, v160, 10, v222
	v_ashrrev_i32_e32 v223, 31, v222
	v_lshlrev_b64 v[222:223], 1, v[222:223]
	v_lshl_add_u64 v[220:221], s[40:41], 0, v[222:223]
	global_load_dwordx2 v[162:163], v[220:221], off
	global_load_dwordx2 v[164:165], v[220:221], off offset:16
	global_load_dwordx2 v[166:167], v[220:221], off offset:32
	global_load_dwordx2 v[168:169], v[220:221], off offset:48
	global_load_dwordx2 v[170:171], v[220:221], off offset:64
	global_load_dwordx2 v[172:173], v[220:221], off offset:80
	global_load_dwordx2 v[174:175], v[220:221], off offset:96
	global_load_dwordx2 v[176:177], v[220:221], off offset:112
	global_load_dwordx2 v[178:179], v[220:221], off offset:128
	global_load_dwordx2 v[180:181], v[220:221], off offset:144
	global_load_dwordx2 v[182:183], v[220:221], off offset:160
	global_load_dwordx2 v[184:185], v[220:221], off offset:176
	global_load_dwordx2 v[186:187], v[220:221], off offset:192
	global_load_dwordx2 v[188:189], v[220:221], off offset:208
	global_load_dwordx2 v[190:191], v[220:221], off offset:224
	global_load_dwordx2 v[192:193], v[220:221], off offset:240
	ds_read_b64_tr_b16 v[80:81], v246 offset:0
	ds_read_b64_tr_b16 v[82:83], v246 offset:0x100
	ds_read_b64_tr_b16 v[84:85], v246 offset:0x1000
	ds_read_b64_tr_b16 v[86:87], v246 offset:0x1100
	ds_read_b64_tr_b16 v[88:89], v246 offset:0x2000
	ds_read_b64_tr_b16 v[90:91], v246 offset:0x2100
	ds_read_b64_tr_b16 v[92:93], v246 offset:0x3000
	ds_read_b64_tr_b16 v[94:95], v246 offset:0x3100
	ds_read_b64_tr_b16 v[96:97], v246 offset:0x200
	ds_read_b64_tr_b16 v[98:99], v246 offset:0x300
	ds_read_b64_tr_b16 v[100:101], v246 offset:0x1200
	ds_read_b64_tr_b16 v[102:103], v246 offset:0x1300
	ds_read_b64_tr_b16 v[104:105], v246 offset:0x2200
	ds_read_b64_tr_b16 v[106:107], v246 offset:0x2300
	ds_read_b64_tr_b16 v[108:109], v246 offset:0x3200
	ds_read_b64_tr_b16 v[110:111], v246 offset:0x3300
	s_waitcnt lgkmcnt(8)
	s_nop 1
	v_mfma_f32_32x32x16_bf16 v[48:63], v[80:83], v[64:67], v[48:63]
	v_mfma_f32_32x32x16_bf16 v[48:63], v[84:87], v[68:71], v[48:63]
	v_mfma_f32_32x32x16_bf16 v[48:63], v[88:91], v[72:75], v[48:63]
	v_mfma_f32_32x32x16_bf16 v[48:63], v[92:95], v[76:79], v[48:63]
	ds_read_b64_tr_b16 v[80:81], v246 offset:0x400
	ds_read_b64_tr_b16 v[82:83], v246 offset:0x500
	ds_read_b64_tr_b16 v[84:85], v246 offset:0x1400
	ds_read_b64_tr_b16 v[86:87], v246 offset:0x1500
	ds_read_b64_tr_b16 v[88:89], v246 offset:0x2400
	ds_read_b64_tr_b16 v[90:91], v246 offset:0x2500
	ds_read_b64_tr_b16 v[92:93], v246 offset:0x3400
	ds_read_b64_tr_b16 v[94:95], v246 offset:0x3500
	s_waitcnt lgkmcnt(8)
; #define SBAR() __builtin_amdgcn_sched_barrier(0)
; __device__ __forceinline__ unsigned cvtpk(float lo, float hi) { return pg8::cvt_pk_bf16(lo, hi); }
; #define PV_RD2(D0, X) const s16x4 X##l0 = tr_read<v_rd_off2(D0, 0, 0)>(vb), X##h0 = tr_read<v_rd_off2(D0, 0, 1)>(vb), X##l1 = tr_read<v_rd_off2(D0, 1, 0)>(vb), X##h1 = tr_read<v_rd_off2(D0, 1, 1)>(vb), \
;                               X##l2 = tr_read<v_rd_off2(D0, 2, 0)>(vb), X##h2 = tr_read<v_rd_off2(D0, 2, 1)>(vb), X##l3 = tr_read<v_rd_off2(D0, 3, 0)>(vb), X##h3 = tr_read<v_rd_off2(D0, 3, 1)>(vb)
; __device__ __forceinline__ void pv_d02(f32x16* o, int vb, bf16x8 pa0, bf16x8 pa1, bf16x8 pa2, bf16x8 pa3) {
;   PV_RD2(0, a);
;   PV_RD2(1, b); asm volatile("s_waitcnt lgkmcnt(8)" ::: "memory"); SBAR(); PV_MM2(o[0], a); SBAR();
;   PV_RD2(2, c); asm volatile("s_waitcnt lgkmcnt(8)" ::: "memory"); SBAR(); PV_MM2(o[1], b); SBAR();
;   PV_RD2(3, d); asm volatile("s_waitcnt lgkmcnt(8)" ::: "memory"); SBAR(); PV_MM2(o[2], c); SBAR();
;   asm volatile("s_waitcnt lgkmcnt(0)" ::: "memory"); SBAR(); PV_MM2(o[3], d);
; }
; __device__ __forceinline__ void attn_dense_body(const bf16* Qb, const bf16* __restrict__ Kh, const bf16* __restrict__ Vh, const bf16* __restrict__ Zb, ...
;     ...
;   { auto rr = __builtin_amdgcn_permlane32_swap(__float_as_uint(l_reg), __float_as_uint(l_reg), false, false); l_reg = __uint_as_float(rr[0]) + __uint_as_float(rr[1]); }
;   const float rl = __builtin_amdgcn_rcpf(l_reg);
;   { int lb = (wid * QBLK + r32) * LDO + 4 * hi; asm volatile("" : "+v"(lb));
;     unsigned short* Ow = (unsigned short*)Ob + lb; const unsigned short* Zw = (const unsigned short*)Zb + lb;
; #pragma unroll
;     for (int d0 = 0; d0 < 4; ++d0)
; #pragma unroll
;       for (int g = 0; g < 4; ++g) { const int co = d0 * 32 + 8 * g; const unsigned long long zz = *(const unsigned long long*)(Zw + co);
;         const float z0 = __uint_as_float((unsigned)(zz << 16)), z1 = __uint_as_float((unsigned)zz & 0xffff0000u), z2 = __uint_as_float((unsigned)(zz >> 32) << 16), z3 = __uint_as_float((unsigned)(zz >> 32) & 0xffff0000u);
;         const unsigned w0 = cvtpk(o[d0][4 * g + 0] * rl * z0, o[d0][4 * g + 1] * rl * z1), w1 = cvtpk(o[d0][4 * g + 2] * rl * z2, o[d0][4 * g + 3] * rl * z3);
	v_mfma_f32_32x32x16_bf16 v[32:47], v[96:99], v[64:67], v[32:47]
	v_mfma_f32_32x32x16_bf16 v[32:47], v[100:103], v[68:71], v[32:47]
	v_mfma_f32_32x32x16_bf16 v[32:47], v[104:107], v[72:75], v[32:47]
	v_mfma_f32_32x32x16_bf16 v[32:47], v[108:111], v[76:79], v[32:47]
	ds_read_b64_tr_b16 v[96:97], v246 offset:0x600
	ds_read_b64_tr_b16 v[98:99], v246 offset:0x700
	ds_read_b64_tr_b16 v[100:101], v246 offset:0x1600
	ds_read_b64_tr_b16 v[102:103], v246 offset:0x1700
	ds_read_b64_tr_b16 v[104:105], v246 offset:0x2600
	ds_read_b64_tr_b16 v[106:107], v246 offset:0x2700
	ds_read_b64_tr_b16 v[108:109], v246 offset:0x3600
	ds_read_b64_tr_b16 v[110:111], v246 offset:0x3700
	s_waitcnt lgkmcnt(8)
	v_mfma_f32_32x32x16_bf16 v[16:31], v[80:83], v[64:67], v[16:31]
	v_mfma_f32_32x32x16_bf16 v[16:31], v[84:87], v[68:71], v[16:31]
	v_mfma_f32_32x32x16_bf16 v[16:31], v[88:91], v[72:75], v[16:31]
	v_mfma_f32_32x32x16_bf16 v[16:31], v[92:95], v[76:79], v[16:31]
	s_waitcnt lgkmcnt(0)
	v_mfma_f32_32x32x16_bf16 v[0:15], v[96:99], v[64:67], v[0:15]
	v_mov_b32_e32 v64, v112
	s_nop 1
	v_permlane32_swap_b32_e32 v112, v64
	v_add_f32_e32 v64, v112, v64
	s_add_i32 s51, s51, s62
	s_cmp_ge_i32 s51, s6
	v_mfma_f32_32x32x16_bf16 v[0:15], v[100:103], v[68:71], v[0:15]
	v_rcp_f32_e32 v68, v64
	v_lshlrev_b32_e32 v64, 2, v245
	v_lshl_add_u32 v64, v160, 10, v64
	v_ashrrev_i32_e32 v65, 31, v64
	v_lshlrev_b64 v[66:67], 1, v[64:65]
	v_lshl_add_u64 v[64:65], s[24:25], 0, v[66:67]
	v_mfma_f32_32x32x16_bf16 v[0:15], v[104:107], v[72:75], v[0:15]
	v_mfma_f32_32x32x16_bf16 v[0:15], v[108:111], v[76:79], v[0:15]
	v_mul_f32_e32 v48, v48, v68
	v_mul_f32_e32 v49, v49, v68
	v_mul_f32_e32 v50, v50, v68
	v_mul_f32_e32 v51, v51, v68
	v_mul_f32_e32 v52, v52, v68
	v_mul_f32_e32 v53, v53, v68
	v_mul_f32_e32 v54, v54, v68
	v_mul_f32_e32 v55, v55, v68
	v_mul_f32_e32 v56, v56, v68
	v_mul_f32_e32 v57, v57, v68
	v_mul_f32_e32 v58, v58, v68
	v_mul_f32_e32 v59, v59, v68
	v_mul_f32_e32 v60, v60, v68
	v_mul_f32_e32 v61, v61, v68
	v_mul_f32_e32 v62, v62, v68
	v_mul_f32_e32 v63, v63, v68
	v_mul_f32_e32 v32, v32, v68
	v_mul_f32_e32 v33, v33, v68
	v_mul_f32_e32 v34, v34, v68
	v_mul_f32_e32 v35, v35, v68
	v_mul_f32_e32 v36, v36, v68
	v_mul_f32_e32 v37, v37, v68
	v_mul_f32_e32 v38, v38, v68
	v_mul_f32_e32 v39, v39, v68
	v_mul_f32_e32 v40, v40, v68
	v_mul_f32_e32 v41, v41, v68
	v_mul_f32_e32 v42, v42, v68
	v_mul_f32_e32 v43, v43, v68
	v_mul_f32_e32 v44, v44, v68
	v_mul_f32_e32 v45, v45, v68
	v_mul_f32_e32 v46, v46, v68
	v_mul_f32_e32 v47, v47, v68
	v_mul_f32_e32 v16, v16, v68
	v_mul_f32_e32 v17, v17, v68
	v_mul_f32_e32 v18, v18, v68
	v_mul_f32_e32 v19, v19, v68
	v_mul_f32_e32 v20, v20, v68
	v_mul_f32_e32 v21, v21, v68
	v_mul_f32_e32 v22, v22, v68
	v_mul_f32_e32 v23, v23, v68
	v_mul_f32_e32 v24, v24, v68
	v_mul_f32_e32 v25, v25, v68
	v_mul_f32_e32 v26, v26, v68
	v_mul_f32_e32 v27, v27, v68
	v_mul_f32_e32 v28, v28, v68
	v_mul_f32_e32 v29, v29, v68
	v_mul_f32_e32 v30, v30, v68
	v_mul_f32_e32 v31, v31, v68
	v_mul_f32_e32 v0, v0, v68
	v_mul_f32_e32 v1, v1, v68
	v_mul_f32_e32 v2, v2, v68
	v_mul_f32_e32 v3, v3, v68
	v_mul_f32_e32 v4, v4, v68
	v_mul_f32_e32 v5, v5, v68
	v_mul_f32_e32 v6, v6, v68
	v_mul_f32_e32 v7, v7, v68
	v_mul_f32_e32 v8, v8, v68
	v_mul_f32_e32 v9, v9, v68
	v_mul_f32_e32 v10, v10, v68
	v_mul_f32_e32 v11, v11, v68
	v_mul_f32_e32 v12, v12, v68
	v_mul_f32_e32 v13, v13, v68
	v_mul_f32_e32 v14, v14, v68
	v_mul_f32_e32 v15, v15, v68
	s_waitcnt vmcnt(0)
; __device__ __forceinline__ unsigned cvtpk(float lo, float hi) { return pg8::cvt_pk_bf16(lo, hi); }
; __device__ __forceinline__ void attn_dense_body(const bf16* Qb, const bf16* __restrict__ Kh, const bf16* __restrict__ Vh, const bf16* __restrict__ Zb, ...
;     ...
;   { int lb = (wid * QBLK + r32) * LDO + 4 * hi; asm volatile("" : "+v"(lb));
;     unsigned short* Ow = (unsigned short*)Ob + lb; const unsigned short* Zw = (const unsigned short*)Zb + lb;
; #pragma unroll
;     for (int d0 = 0; d0 < 4; ++d0)
; #pragma unroll
;       for (int g = 0; g < 4; ++g) { const int co = d0 * 32 + 8 * g; const unsigned long long zz = *(const unsigned long long*)(Zw + co);
;         const float z0 = __uint_as_float((unsigned)(zz << 16)), z1 = __uint_as_float((unsigned)zz & 0xffff0000u), z2 = __uint_as_float((unsigned)(zz >> 32) << 16), z3 = __uint_as_float((unsigned)(zz >> 32) & 0xffff0000u);
;         const unsigned w0 = cvtpk(o[d0][4 * g + 0] * rl * z0, o[d0][4 * g + 1] * rl * z1), w1 = cvtpk(o[d0][4 * g + 2] * rl * z2, o[d0][4 * g + 3] * rl * z3);
;         *(unsigned long long*)(Ow + co) = (unsigned long long)w0 | ((unsigned long long)w1 << 32); } }
	v_lshlrev_b32_e32 v194, 16, v162
	v_and_b32_e32 v195, 0xffff0000, v162
	v_lshlrev_b32_e32 v196, 16, v163
	v_and_b32_e32 v197, 0xffff0000, v163
	v_mul_f32_e32 v48, v48, v194
	v_mul_f32_e32 v49, v49, v195
	v_mul_f32_e32 v50, v50, v196
	v_mul_f32_e32 v51, v51, v197
	v_cvt_pk_bf16_f32 v48, v48, v49
	v_cvt_pk_bf16_f32 v49, v50, v51
	global_store_dwordx2 v[64:65], v[48:49], off
	v_lshlrev_b32_e32 v194, 16, v164
	v_and_b32_e32 v195, 0xffff0000, v164
	v_lshlrev_b32_e32 v196, 16, v165
	v_and_b32_e32 v197, 0xffff0000, v165
	v_mul_f32_e32 v52, v52, v194
	v_mul_f32_e32 v53, v53, v195
	v_mul_f32_e32 v54, v54, v196
	v_mul_f32_e32 v55, v55, v197
	v_cvt_pk_bf16_f32 v52, v52, v53
	v_cvt_pk_bf16_f32 v53, v54, v55
	global_store_dwordx2 v[64:65], v[52:53], off offset:16
	v_lshlrev_b32_e32 v194, 16, v166
	v_and_b32_e32 v195, 0xffff0000, v166
	v_lshlrev_b32_e32 v196, 16, v167
	v_and_b32_e32 v197, 0xffff0000, v167
	v_mul_f32_e32 v56, v56, v194
	v_mul_f32_e32 v57, v57, v195
	v_mul_f32_e32 v58, v58, v196
	v_mul_f32_e32 v59, v59, v197
	v_cvt_pk_bf16_f32 v56, v56, v57
	v_cvt_pk_bf16_f32 v57, v58, v59
	global_store_dwordx2 v[64:65], v[56:57], off offset:32
	v_lshlrev_b32_e32 v194, 16, v168
	v_and_b32_e32 v195, 0xffff0000, v168
	v_lshlrev_b32_e32 v196, 16, v169
	v_and_b32_e32 v197, 0xffff0000, v169
	v_mul_f32_e32 v60, v60, v194
	v_mul_f32_e32 v61, v61, v195
	v_mul_f32_e32 v62, v62, v196
	v_mul_f32_e32 v63, v63, v197
	v_cvt_pk_bf16_f32 v60, v60, v61
	v_cvt_pk_bf16_f32 v61, v62, v63
	global_store_dwordx2 v[64:65], v[60:61], off offset:48
	v_lshlrev_b32_e32 v194, 16, v170
	v_and_b32_e32 v195, 0xffff0000, v170
	v_lshlrev_b32_e32 v196, 16, v171
	v_and_b32_e32 v197, 0xffff0000, v171
	v_mul_f32_e32 v32, v32, v194
	v_mul_f32_e32 v33, v33, v195
	v_mul_f32_e32 v34, v34, v196
	v_mul_f32_e32 v35, v35, v197
	v_cvt_pk_bf16_f32 v32, v32, v33
	v_cvt_pk_bf16_f32 v33, v34, v35
	global_store_dwordx2 v[64:65], v[32:33], off offset:64
	v_lshlrev_b32_e32 v194, 16, v172
	v_and_b32_e32 v195, 0xffff0000, v172
	v_lshlrev_b32_e32 v196, 16, v173
	v_and_b32_e32 v197, 0xffff0000, v173
	v_mul_f32_e32 v36, v36, v194
	v_mul_f32_e32 v37, v37, v195
	v_mul_f32_e32 v38, v38, v196
	v_mul_f32_e32 v39, v39, v197
	v_cvt_pk_bf16_f32 v36, v36, v37
	v_cvt_pk_bf16_f32 v37, v38, v39
	global_store_dwordx2 v[64:65], v[36:37], off offset:80
	v_lshlrev_b32_e32 v194, 16, v174
	v_and_b32_e32 v195, 0xffff0000, v174
	v_lshlrev_b32_e32 v196, 16, v175
	v_and_b32_e32 v197, 0xffff0000, v175
	v_mul_f32_e32 v40, v40, v194
	v_mul_f32_e32 v41, v41, v195
	v_mul_f32_e32 v42, v42, v196
	v_mul_f32_e32 v43, v43, v197
	v_cvt_pk_bf16_f32 v40, v40, v41
	v_cvt_pk_bf16_f32 v41, v42, v43
	global_store_dwordx2 v[64:65], v[40:41], off offset:96
	v_lshlrev_b32_e32 v194, 16, v176
	v_and_b32_e32 v195, 0xffff0000, v176
	v_lshlrev_b32_e32 v196, 16, v177
	v_and_b32_e32 v197, 0xffff0000, v177
	v_mul_f32_e32 v44, v44, v194
	v_mul_f32_e32 v45, v45, v195
	v_mul_f32_e32 v46, v46, v196
	v_mul_f32_e32 v47, v47, v197
	v_cvt_pk_bf16_f32 v44, v44, v45
	v_cvt_pk_bf16_f32 v45, v46, v47
	global_store_dwordx2 v[64:65], v[44:45], off offset:112
	v_lshlrev_b32_e32 v194, 16, v178
	v_and_b32_e32 v195, 0xffff0000, v178
	v_lshlrev_b32_e32 v196, 16, v179
	v_and_b32_e32 v197, 0xffff0000, v179
	v_mul_f32_e32 v16, v16, v194
	v_mul_f32_e32 v17, v17, v195
	v_mul_f32_e32 v18, v18, v196
	v_mul_f32_e32 v19, v19, v197
	v_cvt_pk_bf16_f32 v16, v16, v17
	v_cvt_pk_bf16_f32 v17, v18, v19
	global_store_dwordx2 v[64:65], v[16:17], off offset:128
	v_lshlrev_b32_e32 v194, 16, v180
	v_and_b32_e32 v195, 0xffff0000, v180
	v_lshlrev_b32_e32 v196, 16, v181
	v_and_b32_e32 v197, 0xffff0000, v181
	v_mul_f32_e32 v20, v20, v194
	v_mul_f32_e32 v21, v21, v195
	v_mul_f32_e32 v22, v22, v196
	v_mul_f32_e32 v23, v23, v197
	v_cvt_pk_bf16_f32 v20, v20, v21
	v_cvt_pk_bf16_f32 v21, v22, v23
	global_store_dwordx2 v[64:65], v[20:21], off offset:144
	v_lshlrev_b32_e32 v194, 16, v182
	v_and_b32_e32 v195, 0xffff0000, v182
	v_lshlrev_b32_e32 v196, 16, v183
	v_and_b32_e32 v197, 0xffff0000, v183
	v_mul_f32_e32 v24, v24, v194
	v_mul_f32_e32 v25, v25, v195
	v_mul_f32_e32 v26, v26, v196
	v_mul_f32_e32 v27, v27, v197
	v_cvt_pk_bf16_f32 v24, v24, v25
	v_cvt_pk_bf16_f32 v25, v26, v27
	global_store_dwordx2 v[64:65], v[24:25], off offset:160
	v_lshlrev_b32_e32 v194, 16, v184
	v_and_b32_e32 v195, 0xffff0000, v184
	v_lshlrev_b32_e32 v196, 16, v185
	v_and_b32_e32 v197, 0xffff0000, v185
	v_mul_f32_e32 v28, v28, v194
	v_mul_f32_e32 v29, v29, v195
	v_mul_f32_e32 v30, v30, v196
	v_mul_f32_e32 v31, v31, v197
	v_cvt_pk_bf16_f32 v28, v28, v29
	v_cvt_pk_bf16_f32 v29, v30, v31
	global_store_dwordx2 v[64:65], v[28:29], off offset:176
	v_lshlrev_b32_e32 v194, 16, v186
	v_and_b32_e32 v195, 0xffff0000, v186
	v_lshlrev_b32_e32 v196, 16, v187
	v_and_b32_e32 v197, 0xffff0000, v187
	v_mul_f32_e32 v0, v0, v194
	v_mul_f32_e32 v1, v1, v195
	v_mul_f32_e32 v2, v2, v196
	v_mul_f32_e32 v3, v3, v197
	v_cvt_pk_bf16_f32 v0, v0, v1
	v_cvt_pk_bf16_f32 v1, v2, v3
	global_store_dwordx2 v[64:65], v[0:1], off offset:192
	v_lshlrev_b32_e32 v194, 16, v188
	v_and_b32_e32 v195, 0xffff0000, v188
	v_lshlrev_b32_e32 v196, 16, v189
	v_and_b32_e32 v197, 0xffff0000, v189
	v_mul_f32_e32 v4, v4, v194
	v_mul_f32_e32 v5, v5, v195
	v_mul_f32_e32 v6, v6, v196
	v_mul_f32_e32 v7, v7, v197
	v_cvt_pk_bf16_f32 v4, v4, v5
	v_cvt_pk_bf16_f32 v5, v6, v7
	global_store_dwordx2 v[64:65], v[4:5], off offset:208
	v_lshlrev_b32_e32 v194, 16, v190
	v_and_b32_e32 v195, 0xffff0000, v190
	v_lshlrev_b32_e32 v196, 16, v191
	v_and_b32_e32 v197, 0xffff0000, v191
	v_mul_f32_e32 v8, v8, v194
	v_mul_f32_e32 v9, v9, v195
	v_mul_f32_e32 v10, v10, v196
	v_mul_f32_e32 v11, v11, v197
	v_cvt_pk_bf16_f32 v8, v8, v9
	v_cvt_pk_bf16_f32 v9, v10, v11
	global_store_dwordx2 v[64:65], v[8:9], off offset:224
	v_lshlrev_b32_e32 v194, 16, v192
	v_and_b32_e32 v195, 0xffff0000, v192
	v_lshlrev_b32_e32 v196, 16, v193
	v_and_b32_e32 v197, 0xffff0000, v193
	v_mul_f32_e32 v12, v12, v194
	v_mul_f32_e32 v13, v13, v195
	v_mul_f32_e32 v14, v14, v196
	v_mul_f32_e32 v15, v15, v197
	v_cvt_pk_bf16_f32 v12, v12, v13
	v_cvt_pk_bf16_f32 v13, v14, v15
	global_store_dwordx2 v[64:65], v[12:13], off offset:240
	s_cbranch_scc0 .LBB0_112
	v_readlane_b32 s84, v255, 16
	v_readlane_b32 s85, v255, 17
	v_readlane_b32 s86, v255, 18
	v_readlane_b32 s87, v255, 19
	s_nop 3
